# head1: stack4 + attention steady loop step 1 opens with its first MFMA (resident operands); the 5 adds + 2 cvts that preceded it follow it
# speedup vs baseline: 1.0199x; 1.0199x over previous
.LBB0_413:
	s_mov_b32 s16, s26
	s_mov_b32 s2, s18
	s_mov_b32 s3, s24
	v_lshl_add_u32 v69, s17, 1, v232
	ds_read_b64_tr_b16 v[76:77], v69 offset:24576
	ds_read_b64_tr_b16 v[78:79], v69 offset:25088
	s_waitcnt lgkmcnt(9)
	v_mfma_f32_32x32x16_bf16 v[132:147], v[208:211], v[176:179], 0
	v_add_f32_e32 v72, v100, v101
	v_add_f32_e32 v72, v102, v72
	v_add_f32_e32 v72, v103, v72
	v_add_f32_e32 v72, v104, v72
	v_add_f32_e32 v72, v105, v72
	v_cvt_pk_bf16_f32 v160, v100, v101
	v_cvt_pk_bf16_f32 v161, v102, v103
	v_add_f32_e32 v72, v106, v72
	v_add_f32_e32 v72, v107, v72
	v_add_f32_e32 v72, v108, v72
	v_add_f32_e32 v72, v109, v72
	v_cvt_pk_bf16_f32 v162, v104, v105
	v_cvt_pk_bf16_f32 v163, v106, v107
	s_waitcnt lgkmcnt(8)
	v_mfma_f32_32x32x16_bf16 v[116:131], v[200:203], v[176:179], 0
	ds_read_b64_tr_b16 v[80:81], v69 offset:25600
	ds_read_b64_tr_b16 v[82:83], v69 offset:26112
	v_add_f32_e32 v72, v110, v72
	v_add_f32_e32 v72, v111, v72
	v_add_f32_e32 v72, v112, v72
	v_add_f32_e32 v72, v113, v72
	v_cvt_pk_bf16_f32 v156, v108, v109
	v_cvt_pk_bf16_f32 v157, v110, v111
	s_waitcnt lgkmcnt(9)
	v_mfma_f32_32x32x16_bf16 v[132:147], v[204:207], v[172:175], v[132:147]
	v_add_f32_e32 v72, v114, v72
	v_add_f32_e32 v72, v115, v72
	v_add_f32_e32 v72, v84, v72
	v_add_f32_e32 v72, v85, v72
	v_cvt_pk_bf16_f32 v158, v112, v113
	v_cvt_pk_bf16_f32 v159, v114, v115
	s_waitcnt lgkmcnt(8)
	v_mfma_f32_32x32x16_bf16 v[116:131], v[196:199], v[172:175], v[116:131]
	ds_read_b64_tr_b16 v[100:101], v69 offset:26624
	ds_read_b64_tr_b16 v[102:103], v69 offset:27136
	v_add_f32_e32 v72, v86, v72
	v_add_f32_e32 v72, v87, v72
	v_add_f32_e32 v72, v88, v72
	v_add_f32_e32 v72, v89, v72
	v_cvt_pk_bf16_f32 v152, v84, v85
	v_cvt_pk_bf16_f32 v153, v86, v87
	s_waitcnt lgkmcnt(9)
	v_mfma_f32_32x32x16_bf16 v[132:147], v[192:195], v[168:171], v[132:147]
	v_add_f32_e32 v72, v90, v72
	v_add_f32_e32 v72, v91, v72
	v_add_f32_e32 v72, v92, v72
	v_add_f32_e32 v72, v93, v72
	v_cvt_pk_bf16_f32 v154, v88, v89
	v_cvt_pk_bf16_f32 v155, v90, v91
	s_waitcnt lgkmcnt(8)
	v_mfma_f32_32x32x16_bf16 v[116:131], v[188:191], v[168:171], v[116:131]
	ds_read_b64_tr_b16 v[84:85], v69 offset:27648
	ds_read_b64_tr_b16 v[86:87], v69 offset:28160
	v_add_f32_e32 v72, v94, v72
	v_add_f32_e32 v72, v95, v72
	v_add_f32_e32 v72, v96, v72
	v_add_f32_e32 v72, v97, v72
	v_cvt_pk_bf16_f32 v148, v92, v93
	v_cvt_pk_bf16_f32 v149, v94, v95
	s_waitcnt lgkmcnt(9)
	v_mfma_f32_32x32x16_bf16 v[132:147], v[184:187], v[164:167], v[132:147]
	v_add_f32_e32 v72, v98, v72
	v_add_f32_e32 v72, v99, v72
	v_add_f32_e32 v72, 0, v72
	v_cvt_pk_bf16_f32 v150, v96, v97
	v_cvt_pk_bf16_f32 v151, v98, v99
	s_waitcnt lgkmcnt(8)
	v_mfma_f32_32x32x16_bf16 v[116:131], v[180:183], v[164:167], v[116:131]
	v_lshl_add_u64 v[74:75], v[0:1], 0, s[14:15]
	v_add_f32_e32 v68, v68, v72
	s_add_i32 m0, s24, s0
	v_lshl_add_u64 v[72:73], v[74:75], 0, s[76:77]
	global_load_lds_dwordx4 v[72:73], off
	s_lshl_b32 s17, s26, 1
	s_add_i32 s17, s17, s1
	s_mov_b32 m0, s17
	v_lshl_add_u64 v[72:73], v[70:71], 0, s[14:15]
	v_lshl_add_u64 v[88:89], v[72:73], 0, s[90:91]
	global_load_lds_dwordx4 v[88:89], off
	s_add_i32 m0, s17, 0x2000
	v_lshl_add_u64 v[88:89], v[72:73], 0, s[92:93]
	global_load_lds_dwordx4 v[88:89], off
	s_waitcnt lgkmcnt(6)
	v_mfma_f32_32x32x16_bf16 v[36:51], v[160:163], v[76:79], v[36:51]
	v_exp_f32_e32 v132, v132
	v_exp_f32_e32 v133, v133
	ds_read_b64_tr_b16 v[76:77], v69 offset:28672
	ds_read_b64_tr_b16 v[78:79], v69 offset:29184
	s_waitcnt lgkmcnt(6)
	v_mfma_f32_32x32x16_bf16 v[36:51], v[156:159], v[80:83], v[36:51]
	v_exp_f32_e32 v134, v134
	v_exp_f32_e32 v135, v135
	ds_read_b64_tr_b16 v[80:81], v69 offset:29696
	ds_read_b64_tr_b16 v[82:83], v69 offset:30208
	s_waitcnt lgkmcnt(6)
	v_mfma_f32_32x32x16_bf16 v[36:51], v[152:155], v[100:103], v[36:51]
	v_exp_f32_e32 v136, v136
	v_exp_f32_e32 v137, v137
	ds_read_b64_tr_b16 v[88:89], v69 offset:30720
	ds_read_b64_tr_b16 v[90:91], v69 offset:31232
	s_waitcnt lgkmcnt(6)
	v_mfma_f32_32x32x16_bf16 v[36:51], v[148:151], v[84:87], v[36:51]
	v_exp_f32_e32 v138, v138
	v_exp_f32_e32 v139, v139
	ds_read_b64_tr_b16 v[84:85], v69 offset:31744
	ds_read_b64_tr_b16 v[86:87], v69 offset:32256
	s_waitcnt lgkmcnt(6)
	v_mfma_f32_32x32x16_bf16 v[52:67], v[160:163], v[76:79], v[52:67]
	v_exp_f32_e32 v140, v140
	v_exp_f32_e32 v141, v141
	ds_read_b64_tr_b16 v[76:77], v69 offset:32768
	ds_read_b64_tr_b16 v[78:79], v69 offset:33280
	s_waitcnt lgkmcnt(6)
	v_mfma_f32_32x32x16_bf16 v[52:67], v[156:159], v[80:83], v[52:67]
	v_exp_f32_e32 v142, v142
	v_exp_f32_e32 v143, v143
	ds_read_b64_tr_b16 v[80:81], v69 offset:33792
	ds_read_b64_tr_b16 v[82:83], v69 offset:34304
	s_waitcnt lgkmcnt(6)
	v_mfma_f32_32x32x16_bf16 v[52:67], v[152:155], v[88:91], v[52:67]
	v_exp_f32_e32 v144, v144
	v_exp_f32_e32 v145, v145
	ds_read_b64_tr_b16 v[88:89], v69 offset:34816
	ds_read_b64_tr_b16 v[90:91], v69 offset:35328
	s_waitcnt lgkmcnt(6)
	v_mfma_f32_32x32x16_bf16 v[52:67], v[148:151], v[84:87], v[52:67]
	v_exp_f32_e32 v146, v146
	v_exp_f32_e32 v147, v147
	ds_read_b64_tr_b16 v[84:85], v69 offset:35840
	ds_read_b64_tr_b16 v[86:87], v69 offset:36352
	s_waitcnt lgkmcnt(6)
	v_mfma_f32_32x32x16_bf16 v[4:19], v[160:163], v[76:79], v[4:19]
	v_exp_f32_e32 v116, v116
	v_exp_f32_e32 v117, v117
	ds_read_b64_tr_b16 v[76:77], v69 offset:36864
	ds_read_b64_tr_b16 v[78:79], v69 offset:37376
	s_waitcnt lgkmcnt(6)
	v_mfma_f32_32x32x16_bf16 v[4:19], v[156:159], v[80:83], v[4:19]
	v_exp_f32_e32 v118, v118
	v_exp_f32_e32 v119, v119
	ds_read_b64_tr_b16 v[80:81], v69 offset:37888
	ds_read_b64_tr_b16 v[82:83], v69 offset:38400
	s_waitcnt lgkmcnt(6)
	v_mfma_f32_32x32x16_bf16 v[4:19], v[152:155], v[88:91], v[4:19]
	v_exp_f32_e32 v120, v120
	v_exp_f32_e32 v121, v121
	ds_read_b64_tr_b16 v[88:89], v69 offset:38912
	ds_read_b64_tr_b16 v[90:91], v69 offset:39424
	s_waitcnt lgkmcnt(6)
	v_mfma_f32_32x32x16_bf16 v[4:19], v[148:151], v[84:87], v[4:19]
	v_exp_f32_e32 v122, v122
	v_exp_f32_e32 v123, v123
	ds_read_b64_tr_b16 v[84:85], v69 offset:39936
	ds_read_b64_tr_b16 v[86:87], v69 offset:40448
	v_add_u32_e32 v69, s16, v230
	ds_read_b128 v[92:95], v69
	ds_read_b128 v[96:99], v69 offset:512
	s_waitcnt lgkmcnt(8)
	v_mfma_f32_32x32x16_bf16 v[20:35], v[160:163], v[76:79], v[20:35]
	v_exp_f32_e32 v124, v124
	v_exp_f32_e32 v125, v125
	ds_read_b128 v[76:79], v69 offset:2048
	ds_read_b128 v[180:183], v69 offset:2560
	s_waitcnt lgkmcnt(8)
	v_mfma_f32_32x32x16_bf16 v[20:35], v[156:159], v[80:83], v[20:35]
	v_exp_f32_e32 v126, v126
	v_exp_f32_e32 v127, v127
	ds_read_b128 v[80:83], v69 offset:4096
	ds_read_b128 v[184:187], v69 offset:4608
	ds_read_b128 v[188:191], v69 offset:6144
	ds_read_b128 v[192:195], v69 offset:6656
	s_waitcnt lgkmcnt(10)
	v_mfma_f32_32x32x16_bf16 v[20:35], v[152:155], v[88:91], v[20:35]
	v_exp_f32_e32 v128, v128
	v_exp_f32_e32 v129, v129
	s_waitcnt lgkmcnt(8)
	v_mfma_f32_32x32x16_bf16 v[20:35], v[148:151], v[84:87], v[20:35]
	v_exp_f32_e32 v130, v130
	v_exp_f32_e32 v131, v131
	s_add_i32 s17, s26, 0x2000
	s_cmpk_lg_i32 s26, 0x4000
	s_cselect_b32 s24, s17, 0
	v_lshl_add_u32 v69, s3, 1, v232
	s_waitcnt vmcnt(3) lgkmcnt(0)
	s_barrier
	ds_read_b64_tr_b16 v[196:197], v69 offset:24576
	ds_read_b64_tr_b16 v[198:199], v69 offset:25088
	s_waitcnt lgkmcnt(9)
	v_mfma_f32_32x32x16_bf16 v[100:115], v[92:95], v[176:179], 0
	v_add_f32_e32 v84, v132, v133
	v_add_f32_e32 v84, v134, v84
	v_add_f32_e32 v84, v135, v84
	v_add_f32_e32 v84, v136, v84
	v_add_f32_e32 v84, v137, v84
	v_cvt_pk_bf16_f32 v160, v132, v133
	v_cvt_pk_bf16_f32 v161, v134, v135
	v_add_f32_e32 v84, v138, v84
	v_add_f32_e32 v84, v139, v84
	v_add_f32_e32 v84, v140, v84
	v_add_f32_e32 v148, v141, v84
	s_waitcnt lgkmcnt(8)
	v_mfma_f32_32x32x16_bf16 v[84:99], v[96:99], v[176:179], 0
	v_cvt_pk_bf16_f32 v162, v136, v137
	v_cvt_pk_bf16_f32 v163, v138, v139
	ds_read_b64_tr_b16 v[132:133], v69 offset:25600
	ds_read_b64_tr_b16 v[134:135], v69 offset:26112
	s_waitcnt lgkmcnt(9)
	v_mfma_f32_32x32x16_bf16 v[100:115], v[76:79], v[172:175], v[100:115]
	v_add_f32_e32 v76, v142, v148
	v_add_f32_e32 v76, v143, v76
	v_add_f32_e32 v76, v144, v76
	v_add_f32_e32 v76, v145, v76
	v_cvt_pk_bf16_f32 v156, v140, v141
	v_cvt_pk_bf16_f32 v157, v142, v143
	s_waitcnt lgkmcnt(8)
	v_mfma_f32_32x32x16_bf16 v[84:99], v[180:183], v[172:175], v[84:99]
	v_add_f32_e32 v76, v146, v76
	v_add_f32_e32 v76, v147, v76
	v_add_f32_e32 v76, v116, v76
	v_add_f32_e32 v136, v117, v76
	v_cvt_pk_bf16_f32 v158, v144, v145
	v_cvt_pk_bf16_f32 v159, v146, v147
	ds_read_b64_tr_b16 v[76:77], v69 offset:26624
	ds_read_b64_tr_b16 v[78:79], v69 offset:27136
	s_waitcnt lgkmcnt(9)
	v_mfma_f32_32x32x16_bf16 v[100:115], v[80:83], v[168:171], v[100:115]
	v_add_f32_e32 v80, v118, v136
	v_add_f32_e32 v80, v119, v80
	v_add_f32_e32 v80, v120, v80
	v_add_f32_e32 v80, v121, v80
	v_cvt_pk_bf16_f32 v152, v116, v117
	v_cvt_pk_bf16_f32 v153, v118, v119
	s_waitcnt lgkmcnt(8)
	v_mfma_f32_32x32x16_bf16 v[84:99], v[184:187], v[168:171], v[84:99]
	v_add_f32_e32 v80, v122, v80
	v_add_f32_e32 v80, v123, v80
	v_add_f32_e32 v80, v124, v80
	v_add_f32_e32 v116, v125, v80
	v_cvt_pk_bf16_f32 v154, v120, v121
	v_cvt_pk_bf16_f32 v155, v122, v123
	ds_read_b64_tr_b16 v[80:81], v69 offset:27648
	ds_read_b64_tr_b16 v[82:83], v69 offset:28160
	s_waitcnt lgkmcnt(9)
	v_mfma_f32_32x32x16_bf16 v[100:115], v[188:191], v[164:167], v[100:115]
	v_add_f32_e32 v116, v126, v116
	v_add_f32_e32 v116, v127, v116
	v_add_f32_e32 v116, v128, v116
	v_add_f32_e32 v116, v129, v116
	v_cvt_pk_bf16_f32 v148, v124, v125
	v_cvt_pk_bf16_f32 v149, v126, v127
	s_waitcnt lgkmcnt(8)
	v_mfma_f32_32x32x16_bf16 v[84:99], v[192:195], v[164:167], v[84:99]
	v_add_f32_e32 v116, v130, v116
	v_add_f32_e32 v116, v131, v116
	v_add_f32_e32 v116, 0, v116
	v_cvt_pk_bf16_f32 v150, v128, v129
	v_cvt_pk_bf16_f32 v151, v130, v131
	s_add_i32 m0, s26, s0
	v_lshl_add_u64 v[74:75], v[74:75], 0, s[28:29]
	global_load_lds_dwordx4 v[74:75], off
	s_lshl_b32 s3, s24, 1
	s_add_i32 s3, s3, s1
	s_mov_b32 m0, s3
	v_lshl_add_u64 v[74:75], v[72:73], 0, s[66:67]
	global_load_lds_dwordx4 v[74:75], off
	s_add_i32 m0, s3, 0x2000
	v_lshl_add_u64 v[72:73], v[72:73], 0, s[72:73]
	global_load_lds_dwordx4 v[72:73], off
	v_add_f32_e32 v68, v68, v116
	s_waitcnt lgkmcnt(6)
	v_mfma_f32_32x32x16_bf16 v[36:51], v[160:163], v[196:199], v[36:51]
	v_exp_f32_e32 v100, v100
	v_exp_f32_e32 v101, v101
	ds_read_b64_tr_b16 v[72:73], v69 offset:28672
	ds_read_b64_tr_b16 v[74:75], v69 offset:29184
	s_waitcnt lgkmcnt(6)
	v_mfma_f32_32x32x16_bf16 v[36:51], v[156:159], v[132:135], v[36:51]
	v_exp_f32_e32 v102, v102
	v_exp_f32_e32 v103, v103
	ds_read_b64_tr_b16 v[116:117], v69 offset:29696
	ds_read_b64_tr_b16 v[118:119], v69 offset:30208
	s_waitcnt lgkmcnt(6)
	v_mfma_f32_32x32x16_bf16 v[36:51], v[152:155], v[76:79], v[36:51]
	v_exp_f32_e32 v104, v104
	v_exp_f32_e32 v105, v105
	ds_read_b64_tr_b16 v[76:77], v69 offset:30720
	ds_read_b64_tr_b16 v[78:79], v69 offset:31232
	s_waitcnt lgkmcnt(6)
	v_mfma_f32_32x32x16_bf16 v[36:51], v[148:151], v[80:83], v[36:51]
	v_exp_f32_e32 v106, v106
	v_exp_f32_e32 v107, v107
	ds_read_b64_tr_b16 v[80:81], v69 offset:31744
	ds_read_b64_tr_b16 v[82:83], v69 offset:32256
	s_waitcnt lgkmcnt(6)
	v_mfma_f32_32x32x16_bf16 v[52:67], v[160:163], v[72:75], v[52:67]
	v_exp_f32_e32 v108, v108
	v_exp_f32_e32 v109, v109
	ds_read_b64_tr_b16 v[72:73], v69 offset:32768
	ds_read_b64_tr_b16 v[74:75], v69 offset:33280
	s_waitcnt lgkmcnt(6)
	v_mfma_f32_32x32x16_bf16 v[52:67], v[156:159], v[116:119], v[52:67]
	v_exp_f32_e32 v110, v110
	v_exp_f32_e32 v111, v111
	ds_read_b64_tr_b16 v[116:117], v69 offset:33792
	ds_read_b64_tr_b16 v[118:119], v69 offset:34304
	s_waitcnt lgkmcnt(6)
	v_mfma_f32_32x32x16_bf16 v[52:67], v[152:155], v[76:79], v[52:67]
	v_exp_f32_e32 v112, v112
	v_exp_f32_e32 v113, v113
	ds_read_b64_tr_b16 v[76:77], v69 offset:34816
	ds_read_b64_tr_b16 v[78:79], v69 offset:35328
	s_waitcnt lgkmcnt(6)
	v_mfma_f32_32x32x16_bf16 v[52:67], v[148:151], v[80:83], v[52:67]
	v_exp_f32_e32 v114, v114
	v_exp_f32_e32 v115, v115
	ds_read_b64_tr_b16 v[80:81], v69 offset:35840
	ds_read_b64_tr_b16 v[82:83], v69 offset:36352
	s_waitcnt lgkmcnt(6)
	v_mfma_f32_32x32x16_bf16 v[4:19], v[160:163], v[72:75], v[4:19]
	v_exp_f32_e32 v84, v84
	v_exp_f32_e32 v85, v85
	ds_read_b64_tr_b16 v[72:73], v69 offset:36864
	ds_read_b64_tr_b16 v[74:75], v69 offset:37376
	s_waitcnt lgkmcnt(6)
	v_mfma_f32_32x32x16_bf16 v[4:19], v[156:159], v[116:119], v[4:19]
	v_exp_f32_e32 v86, v86
	v_exp_f32_e32 v87, v87
	ds_read_b64_tr_b16 v[116:117], v69 offset:37888
	ds_read_b64_tr_b16 v[118:119], v69 offset:38400
	s_waitcnt lgkmcnt(6)
	v_mfma_f32_32x32x16_bf16 v[4:19], v[152:155], v[76:79], v[4:19]
	v_exp_f32_e32 v88, v88
	v_exp_f32_e32 v89, v89
	ds_read_b64_tr_b16 v[76:77], v69 offset:38912
	ds_read_b64_tr_b16 v[78:79], v69 offset:39424
	s_waitcnt lgkmcnt(6)
	v_mfma_f32_32x32x16_bf16 v[4:19], v[148:151], v[80:83], v[4:19]
	v_exp_f32_e32 v90, v90
	v_exp_f32_e32 v91, v91
	ds_read_b64_tr_b16 v[80:81], v69 offset:39936
	ds_read_b64_tr_b16 v[82:83], v69 offset:40448
	v_add_u32_e32 v69, s24, v230
	ds_read_b128 v[208:211], v69
	ds_read_b128 v[200:203], v69 offset:512
	s_waitcnt lgkmcnt(8)
	v_mfma_f32_32x32x16_bf16 v[20:35], v[160:163], v[72:75], v[20:35]
	v_exp_f32_e32 v92, v92
	v_exp_f32_e32 v93, v93
	ds_read_b128 v[204:207], v69 offset:2048
	ds_read_b128 v[196:199], v69 offset:2560
	s_waitcnt lgkmcnt(8)
	v_mfma_f32_32x32x16_bf16 v[20:35], v[156:159], v[116:119], v[20:35]
	v_exp_f32_e32 v94, v94
	v_exp_f32_e32 v95, v95
	ds_read_b128 v[192:195], v69 offset:4096
	ds_read_b128 v[188:191], v69 offset:4608
	ds_read_b128 v[184:187], v69 offset:6144
	ds_read_b128 v[180:183], v69 offset:6656
	s_waitcnt lgkmcnt(10)
	v_mfma_f32_32x32x16_bf16 v[20:35], v[152:155], v[76:79], v[20:35]
	v_exp_f32_e32 v96, v96
	v_exp_f32_e32 v97, v97
	s_waitcnt lgkmcnt(8)
	v_mfma_f32_32x32x16_bf16 v[20:35], v[148:151], v[80:83], v[20:35]
	v_exp_f32_e32 v98, v98
	v_exp_f32_e32 v99, v99
	s_add_i32 s3, s24, 0x2000
	s_cmpk_lg_i32 s24, 0x4000
	s_cselect_b32 s26, s3, 0
	s_add_i32 s18, s2, 2
	s_add_u32 s14, s14, 0x20000
	s_addc_u32 s15, s15, 0
	s_mov_b32 s17, s16
	s_cmp_ge_u32 s18, s21
	s_waitcnt vmcnt(3) lgkmcnt(0)
	s_barrier
	s_cbranch_scc0 .LBB0_413
	s_add_i32 s64, s2, -3
	s_lshl_b64 s[12:13], s[12:13], 9
	s_add_i32 s2, s64, 1
	s_cmp_lt_u32 s2, s21
	s_cbranch_scc0 .LBB0_441
